# one static s_setprio 1 for waves 0-3 at kernel entry (older half) for comparison with the waves 4-7 variant
# baseline (speedup 1.0000x reference)
_Z10fwd_kernel6Params:
	s_mov_b64 s[92:93], s[0:1]
	v_readfirstlane_b32 s100, v0
	s_nop 3
	s_and_b32 s100, s100, 0x3ff
	s_lshr_b32 s100, s100, 6
	s_cmp_ge_u32 s100, 4
	s_cbranch_scc1 .Lprio_done
	s_setprio 1
